# v22 with the placement-mismatch fall-back path reduced to one masked flag store per wave (main path unchanged)
# speedup vs baseline: 1.0079x; 1.0061x over previous
; __device__ __forceinline__ void xcd_barrier(const XcdBarrier& b) {
;     asm volatile("s_waitcnt vmcnt(0)" ::: "memory");
;     __syncthreads();
.LBB0_553:
	s_or_b64 exec, exec, s[0:1]
	s_getreg_b32 s98, hwreg(HW_REG_XCC_ID, 0, 4)
	s_add_i32 s98, s98, 1
	s_waitcnt vmcnt(0)
	v_cmp_ne_u32_e64 s[100:101], s98, v238
	s_cmp_eq_u64 s[100:101], 0
	s_cbranch_scc1 .Lplace_ok
	v_readlane_b32 s98, v236, 2
	v_readlane_b32 s99, v236, 3
	v_mov_b32_e32 v239, 0x100
	v_mov_b32_e32 v238, 1
	s_mov_b64 s[100:101], exec
	s_mov_b64 exec, 1
	s_nop 2
	global_store_dword v239, v238, s[98:99] sc0 sc1
	s_mov_b64 exec, s[100:101]
